# attention loop: one static s_setprio 1 for waves 4-7 per unit (reset after the unit)
# speedup vs baseline: 1.0003x; 1.0003x over previous
; #define LAS __attribute__((address_space(3)))
; __device__ __forceinline__ void attn_unit(CArgs a, int layer, int unit, LAS unsigned char* lds) {
;     ...
;         const float* khn = a->mla_khn + layer * 96;
;         float gm = fmaxf(fabsf(khn[lane]), fabsf(khn[64 + (lane & 31)]));
; #pragma unroll
;         for (int o = 1; o < 64; o <<= 1) gm = fmaxf(gm, __shfl_xor(gm, o));
;         mref = 1.02f * sqrtf(qn2) * 9.797958971f * gm;
;     }
;     u32x4 kr0, kr1, vr;
;     const int kc0 = tid, kc1 = tid + 512;
;     constexpr int NT = SEQ / 64;
;     auto gloadK = [&](int t) {
;         const bf16_t* kt = Kg + (size_t)t * 64 * 96;
;         kr0 = *(const u32x4*)(kt + kc0 * 8);
;         kr1 = *(const u32x4*)(kt + (kc1 < 768 ? kc1 : 767) * 8);
;     };
;     auto gloadV = [&](int t) { vr = *(const u32x4*)(Vg + (size_t)t * 64 * 64 + tid * 8); };
;     auto lstoreK = [&](int buf) {
;         LAS bf16_t* Kl = (LAS bf16_t*)(lds + AT_K + buf * AT_KB);
;         *(LAS u32x4*)(Kl + (kc0 / 12) * AT_KLD + (kc0 % 12) * 8) = kr0;
;         if (kc1 < 768) *(LAS u32x4*)(Kl + (kc1 / 12) * AT_KLD + (kc1 % 12) * 8) = kr1;
;     };
;     auto lstoreV = [&](int buf) {
;         LAS bf16_t* Vl = (LAS bf16_t*)(lds + AT_V + buf * AT_VB);
;         *(LAS u32x4*)(Vl + (tid >> 3) * AT_VLD + (tid & 7) * 8) = vr;
;     };
;     f32x16 negm;
; #pragma unroll
;     for (int r = 0; r < 16; ++r) negm[r] = -mref;
;     auto qk = [&](int buf, f32x16& p0, f32x16& p1) {
;         const LAS bf16_t* Kl = (const LAS bf16_t*)(lds + AT_K + buf * AT_KB);
; #pragma unroll
;         for (int s = 0; s < 6; ++s) {
;             const bf16x8 k0 = *(const LAS bf16x8*)(Kl + r32 * AT_KLD + 16 * s + 8 * hi);
;             const bf16x8 k1 = *(const LAS bf16x8*)(Kl + (32 + r32) * AT_KLD + 16 * s + 8 * hi);
;             if (s == 0) { p0 = MFMA32(k0, qf[0], negm); p1 = MFMA32(k1, qf[0], negm); }
;             else { p0 = MFMA32(k0, qf[s], p0); p1 = MFMA32(k1, qf[s], p1); }
;         }
;     };
;     __syncthreads();
;     gloadK(0); gloadV(0); lstoreK(0); lstoreV(0); gloadK(1); lstoreK(1);
;     __syncthreads();
;     float lrun = 0.f;
;     f32x16 o0, o1, pA0, pA1, pB0, pB1;
; #pragma unroll
;     for (int r = 0; r < 16; ++r) { o0[r] = 0.f; o1[r] = 0.f; }
;     qk(0, pA0, pA1);
;     auto tile = [&](int t, f32x16& c0, f32x16& c1, f32x16& n0, f32x16& n1) {
;         const int buf = t & 1;
.LBB0_72:
	s_or_b64 exec, exec, s[2:3]
	v_cndmask_b32_e64 v35, v35, v37, s[42:43]
	s_waitcnt lgkmcnt(3)
	v_max_f32_e32 v5, v38, v38
	v_cndmask_b32_e64 v35, v35, v39, s[44:45]
	v_max_f32_e32 v5, v36, v5
	v_mul_f32_e32 v36, 0x37800000, v35
	v_cndmask_b32_e32 v35, v35, v36, vcc
	v_mov_b32_e32 v36, 0x260
	v_cmp_class_f32_e32 vcc, v34, v36
	v_cvt_pk_bf16_f32 v114, v22, v23
	v_lshlrev_b32_e32 v4, 3, v160
	v_cndmask_b32_e32 v34, v35, v34, vcc
	v_mul_f32_e32 v22, 0xbf828f5c, v34
	v_mul_f32_e32 v22, 0x411cc471, v22
	v_mul_f32_e32 v34, v22, v5
	v_mul_u32_u24_e32 v5, 0xd0, v161
	v_lshlrev_b32_e32 v4, 1, v4
	v_add3_u32 v168, 0, v5, v4
	v_cvt_pk_bf16_f32 v115, v24, v25
	s_waitcnt lgkmcnt(0)
	s_barrier
	ds_read_b128 v[22:25], v168
	v_cvt_pk_bf16_f32 v116, v26, v27
	v_cvt_pk_bf16_f32 v117, v28, v29
	v_mov_b32_e32 v35, v34
	v_mov_b32_e32 v36, v34
	v_mov_b32_e32 v37, v34
	v_mov_b32_e32 v38, v34
	v_mov_b32_e32 v39, v34
	v_mov_b32_e32 v40, v34
	v_mov_b32_e32 v41, v34
	v_mov_b32_e32 v42, v34
	v_mov_b32_e32 v43, v34
	v_mov_b32_e32 v44, v34
	v_mov_b32_e32 v45, v34
	v_mov_b32_e32 v46, v34
	v_mov_b32_e32 v47, v34
	v_mov_b32_e32 v48, v34
	v_mov_b32_e32 v49, v34
	ds_read_b128 v[26:29], v168 offset:32
	v_cvt_pk_bf16_f32 v118, v10, v11
	s_waitcnt lgkmcnt(1)
	v_mfma_f32_32x32x16_bf16 v[50:65], v[22:25], v[114:117], v[34:49]
	ds_read_b128 v[22:25], v168 offset:6656
	ds_read_b128 v[102:105], v168 offset:6688
	v_cvt_pk_bf16_f32 v119, v14, v15
	v_cvt_pk_bf16_f32 v120, v18, v19
	v_cvt_pk_bf16_f32 v121, v20, v21
	ds_read_b128 v[18:21], v168 offset:64
	v_cvt_pk_bf16_f32 v122, v90, v91
	v_cvt_pk_bf16_f32 v123, v92, v93
	s_waitcnt lgkmcnt(2)
	v_mfma_f32_32x32x16_bf16 v[66:81], v[22:25], v[114:117], v[34:49]
	v_cvt_pk_bf16_f32 v124, v94, v95
	v_cvt_pk_bf16_f32 v125, v98, v99
	ds_read_b128 v[22:25], v168 offset:96
	v_cvt_pk_bf16_f32 v126, v30, v31
	v_cvt_pk_bf16_f32 v127, v32, v33
	v_cvt_pk_bf16_f32 v128, v82, v83
	v_cvt_pk_bf16_f32 v129, v84, v85
	v_mfma_f32_32x32x16_bf16 v[50:65], v[26:29], v[118:121], v[50:65]
	v_cvt_pk_bf16_f32 v130, v16, v17
	v_cvt_pk_bf16_f32 v131, v86, v87
	v_cvt_pk_bf16_f32 v132, v96, v97
	v_cvt_pk_bf16_f32 v133, v100, v101
	v_cvt_pk_bf16_f32 v134, v6, v7
	v_cvt_pk_bf16_f32 v135, v8, v9
	v_cvt_pk_bf16_f32 v136, v12, v13
	s_waitcnt lgkmcnt(2)
	v_mfma_f32_32x32x16_bf16 v[66:81], v[102:105], v[118:121], v[66:81]
	v_cvt_pk_bf16_f32 v137, v88, v89
	v_lshlrev_b32_e32 v169, 2, v160
	v_lshrrev_b32_e32 v8, 2, v159
	v_and_or_b32 v8, v8, 3, v169
	v_and_b32_e32 v9, 16, v159
	v_lshlrev_b32_e32 v10, 3, v0
	s_add_u32 s2, s60, s22
	s_waitcnt lgkmcnt(1)
	v_mfma_f32_32x32x16_bf16 v[50:65], v[18:21], v[122:125], v[50:65]
	ds_read_b128 v[18:21], v168 offset:6720
	ds_read_b128 v[26:29], v168 offset:6752
	ds_read_b128 v[14:17], v168 offset:160
	ds_read_b128 v[4:7], v168 offset:6816
	v_mad_u32_u24 v8, v8, s82, 0
	v_lshlrev_b32_e32 v9, 1, v9
	v_and_b32_e32 v10, 24, v10
	s_addc_u32 s3, s61, s23
	s_waitcnt lgkmcnt(3)
	v_mfma_f32_32x32x16_bf16 v[66:81], v[18:21], v[122:125], v[66:81]
	ds_read_b128 v[18:21], v168 offset:128
	v_add3_u32 v170, v8, v9, v10
	v_add_u32_e32 v3, 0, v3
	v_lshl_add_u64 v[8:9], v[150:151], 1, s[2:3]
	s_mov_b64 s[2:3], 0x17a02000
	v_mov_b32_e32 v172, 0
	v_lshl_add_u64 v[156:157], v[8:9], 0, s[2:3]
	v_mfma_f32_32x32x16_bf16 v[50:65], v[22:25], v[126:129], v[50:65]
	s_mov_b32 s13, -2
	v_add_u32_e32 v171, v3, v2
	v_mov_b32_e32 v2, 0
	v_mov_b32_e32 v3, v172
	v_mov_b32_e32 v8, v172
	v_mov_b32_e32 v9, v172
	v_mov_b32_e32 v10, v172
	s_waitcnt lgkmcnt(0)
	v_mfma_f32_32x32x16_bf16 v[50:65], v[18:21], v[130:133], v[50:65]
	ds_read_b128 v[18:21], v168 offset:6784
	v_mov_b32_e32 v11, v172
	v_mov_b32_e32 v12, v172
	v_mov_b32_e32 v13, v172
	v_mov_b32_e32 v22, v172
	v_mov_b32_e32 v23, v172
	v_mov_b32_e32 v24, v172
	v_mfma_f32_32x32x16_bf16 v[66:81], v[26:29], v[126:129], v[66:81]
	v_mov_b32_e32 v25, v172
	v_mov_b32_e32 v26, v172
	v_mov_b32_e32 v27, v172
	v_mov_b32_e32 v28, v172
	v_mov_b32_e32 v29, v172
	v_mov_b32_e32 v30, v172
	v_mov_b32_e32 v31, v172
	s_waitcnt lgkmcnt(0)
	v_mfma_f32_32x32x16_bf16 v[66:81], v[18:21], v[130:133], v[66:81]
	v_mov_b32_e32 v18, 0
	v_mov_b32_e32 v19, v172
	v_mov_b32_e32 v20, v172
	v_mov_b32_e32 v21, v172
	v_mov_b32_e32 v32, v172
	v_mov_b32_e32 v33, v172
	v_mfma_f32_32x32x16_bf16 v[50:65], v[14:17], v[134:137], v[50:65]
	v_mov_b32_e32 v14, v172
	v_mov_b32_e32 v15, v172
	v_mov_b32_e32 v16, v172
	v_mov_b32_e32 v17, v172
	v_mfma_f32_32x32x16_bf16 v[66:81], v[4:7], v[134:137], v[66:81]
	v_mov_b32_e32 v4, v172
	v_mov_b32_e32 v5, v172
	v_mov_b32_e32 v6, v172
	v_mov_b32_e32 v7, v172
	v_lshlrev_b32_e32 v175, 1, v154
	s_add_u32 s2, s20, 0x6000
	s_addc_u32 s3, s21, 0
	s_add_u32 s24, s18, 0x2000
	s_addc_u32 s25, s19, 0
	global_load_dwordx4 v[224:227], v152, s[2:3]
	global_load_dwordx4 v[228:231], v175, s[2:3]
	global_load_dwordx4 v[232:235], v152, s[24:25]
	s_mov_b32 s13, 0
	s_and_b64 vcc, exec, s[40:41]
	s_cbranch_vccnz .Lattn_prio_old
	s_setprio 1
.Lattn_prio_old:
	s_nop 0
; __device__ __forceinline__ void attn_unit(CArgs a, int layer, int unit, LAS unsigned char* lds) {
;     ...
;     auto tile = [&](int t, f32x16& c0, f32x16& c1, f32x16& n0, f32x16& n1) {
;         const int buf = t & 1;
;         gloadK(t + 2 < NT ? t + 2 : NT - 1); gloadV(t + 1 < NT ? t + 1 : NT - 1);
;         const LAS bf16_t* Vl = (const LAS bf16_t*)(lds + AT_V + buf * AT_VB);
;         if (t + 1 < NT) qk(buf ^ 1, n0, n1);
;         f32x16 p0, p1;
;         float rs = 0.f;
; #pragma unroll
;         for (int r = 0; r < 16; ++r) { p0[r] = __builtin_amdgcn_exp2f(c0[r]); p1[r] = __builtin_amdgcn_exp2f(c1[r]); rs += p0[r] + p1[r]; }
;         lrun += rs;
;         bf16x8 pf[4];
; #pragma unroll
;         for (int s = 0; s < 2; ++s) {
;             u32x4 w0, w1;
;             w0.x = cvt_pk_bf16(p0[8 * s], p0[8 * s + 1]); w0.y = cvt_pk_bf16(p0[8 * s + 2], p0[8 * s + 3]); w0.z = cvt_pk_bf16(p0[8 * s + 4], p0[8 * s + 5]); w0.w = cvt_pk_bf16(p0[8 * s + 6], p0[8 * s + 7]);
;             w1.x = cvt_pk_bf16(p1[8 * s], p1[8 * s + 1]); w1.y = cvt_pk_bf16(p1[8 * s + 2], p1[8 * s + 3]); w1.z = cvt_pk_bf16(p1[8 * s + 4], p1[8 * s + 5]); w1.w = cvt_pk_bf16(p1[8 * s + 6], p1[8 * s + 7]);
;             pf[s] = __builtin_bit_cast(bf16x8, w0); pf[2 + s] = __builtin_bit_cast(bf16x8, w1);
;         }
; #pragma unroll
;         for (int i = 0; i < 12; ++i) { __builtin_amdgcn_sched_group_barrier(0x008, 1, 0); __builtin_amdgcn_sched_group_barrier(0x002, 9, 0); }
; #pragma unroll
;         for (int s4 = 0; s4 < 4; ++s4) {
;             const int kb = 32 * (s4 >> 1) + 16 * (s4 & 1) + 4 * hi;
;             const LAS bf16_t* vrow = Vl + (kb - 4 * hi + 4 * hi + ((lane & 15) >> 2)) * AT_VLD + 16 * ((lane >> 4) & 1) + 4 * (lane & 3);
;             const v4i16_t a0 = __builtin_amdgcn_ds_read_tr16_b64_v4i16((LAS v4i16_t*)(vrow)), a1 = __builtin_amdgcn_ds_read_tr16_b64_v4i16((LAS v4i16_t*)(vrow + 8 * AT_VLD));
;             const v4i16_t c0 = __builtin_amdgcn_ds_read_tr16_b64_v4i16((LAS v4i16_t*)(vrow + 32)), c1 = __builtin_amdgcn_ds_read_tr16_b64_v4i16((LAS v4i16_t*)(vrow + 8 * AT_VLD + 32));
;             const bf16x8 v0 = __builtin_shufflevector(a0, a1, 0, 1, 2, 3, 4, 5, 6, 7), v1 = __builtin_shufflevector(c0, c1, 0, 1, 2, 3, 4, 5, 6, 7);
;             o0 = MFMA32(pf[s4], v0, o0);
;             o1 = MFMA32(pf[s4], v1, o1);
;         }
;         lstoreK(buf); lstoreV(buf ^ 1);
.Lattn_loop:
	s_add_i32 s12, s13, 3
	s_min_u32 s12, s12, 31
	s_mul_i32 s12, s12, 0x3000
	s_add_u32 s2, s20, s12
	s_addc_u32 s3, s21, 0
	s_add_i32 s12, s13, 2
	s_min_u32 s12, s12, 31
	s_lshl_b32 s12, s12, 13
	s_add_u32 s24, s18, s12
	s_addc_u32 s25, s19, 0
	global_load_dwordx4 v[200:203], v152, s[2:3]
	global_load_dwordx4 v[204:207], v175, s[2:3]
	global_load_dwordx4 v[208:211], v152, s[24:25]
	ds_read_b128 v[138:141], v168 offset:13312
	ds_read_b128 v[142:145], v168 offset:19968
	ds_read_b128 v[146:149], v168 offset:13344
	ds_read_b64_tr_b16 v[212:213], v170 offset:26624
	ds_read_b64_tr_b16 v[214:215], v170 offset:27776
	ds_read_b64_tr_b16 v[216:217], v170 offset:26688
	ds_read_b64_tr_b16 v[218:219], v170 offset:27840
	v_exp_f32_e32 v192, v50
	v_exp_f32_e32 v193, v51
	v_exp_f32_e32 v194, v52
	v_exp_f32_e32 v195, v53
	v_exp_f32_e32 v196, v54
	v_exp_f32_e32 v197, v55
	s_waitcnt lgkmcnt(6)
	v_mfma_f32_32x32x16_bf16 v[98:113], v[138:141], v[114:117], v[34:49]
	ds_read_b128 v[138:141], v168 offset:20000
	v_exp_f32_e32 v198, v56
	v_exp_f32_e32 v199, v57
	v_add_f32_e32 v173, v192, v193
	v_add_f32_e32 v174, v194, v195
	v_add_f32_e32 v173, v173, v196
	v_add_f32_e32 v174, v174, v197
	s_waitcnt lgkmcnt(6)
	v_mfma_f32_32x32x16_bf16 v[82:97], v[142:145], v[114:117], v[34:49]
	ds_read_b128 v[142:145], v168 offset:13376
	v_add_f32_e32 v173, v173, v198
	v_add_f32_e32 v174, v174, v199
	v_cvt_pk_bf16_f32 v176, v192, v193
	v_cvt_pk_bf16_f32 v177, v194, v195
	v_cvt_pk_bf16_f32 v178, v196, v197
	v_cvt_pk_bf16_f32 v179, v198, v199
	s_waitcnt lgkmcnt(6)
	v_mfma_f32_32x32x16_bf16 v[98:113], v[146:149], v[118:121], v[98:113]
	ds_read_b128 v[146:149], v168 offset:20032
	v_exp_f32_e32 v192, v58
	v_exp_f32_e32 v193, v59
	v_exp_f32_e32 v194, v60
	v_exp_f32_e32 v195, v61
	s_waitcnt lgkmcnt(5)
	v_mfma_f32_32x32x16_bf16 v[2:17], v[176:179], v[212:215], v[2:17]
	ds_read_b64_tr_b16 v[220:221], v170 offset:28928
	ds_read_b64_tr_b16 v[222:223], v170 offset:30080
	v_exp_f32_e32 v196, v62
	v_exp_f32_e32 v197, v63
	v_exp_f32_e32 v198, v64
	v_exp_f32_e32 v199, v65
	s_waitcnt lgkmcnt(5)
	v_mfma_f32_32x32x16_bf16 v[18:33], v[176:179], v[216:219], v[18:33]
	ds_read_b64_tr_b16 v[236:237], v170 offset:28992
	ds_read_b64_tr_b16 v[238:239], v170 offset:30144
	v_add_f32_e32 v173, v173, v192
	v_add_f32_e32 v174, v174, v193
	v_add_f32_e32 v173, v173, v194
	v_add_f32_e32 v174, v174, v195
	s_waitcnt lgkmcnt(6)
	v_mfma_f32_32x32x16_bf16 v[82:97], v[138:141], v[118:121], v[82:97]
	ds_read_b128 v[138:141], v168 offset:13408
	v_add_f32_e32 v173, v173, v196
	v_add_f32_e32 v174, v174, v197
	v_add_f32_e32 v173, v173, v198
	v_add_f32_e32 v174, v174, v199
	s_waitcnt lgkmcnt(6)
	v_mfma_f32_32x32x16_bf16 v[98:113], v[142:145], v[122:125], v[98:113]
	ds_read_b128 v[142:145], v168 offset:20064
	v_cvt_pk_bf16_f32 v180, v192, v193
	v_cvt_pk_bf16_f32 v181, v194, v195
	v_cvt_pk_bf16_f32 v182, v196, v197
	v_cvt_pk_bf16_f32 v183, v198, v199
	s_waitcnt lgkmcnt(6)
	v_mfma_f32_32x32x16_bf16 v[82:97], v[146:149], v[122:125], v[82:97]
	ds_read_b128 v[146:149], v168 offset:13440
	v_exp_f32_e32 v192, v66
	v_exp_f32_e32 v193, v67
	v_exp_f32_e32 v194, v68
	v_exp_f32_e32 v195, v69
	s_waitcnt lgkmcnt(5)
	v_mfma_f32_32x32x16_bf16 v[2:17], v[180:183], v[220:223], v[2:17]
	ds_read_b64_tr_b16 v[212:213], v170 offset:31232
	ds_read_b64_tr_b16 v[214:215], v170 offset:32384
	v_exp_f32_e32 v196, v70
	v_exp_f32_e32 v197, v71
	v_exp_f32_e32 v198, v72
	v_exp_f32_e32 v199, v73
	s_waitcnt lgkmcnt(5)
	v_mfma_f32_32x32x16_bf16 v[18:33], v[180:183], v[236:239], v[18:33]
	ds_read_b64_tr_b16 v[216:217], v170 offset:31296
	ds_read_b64_tr_b16 v[218:219], v170 offset:32448
	v_add_f32_e32 v173, v173, v192
	v_add_f32_e32 v174, v174, v193
	v_add_f32_e32 v173, v173, v194
	v_add_f32_e32 v174, v174, v195
	s_waitcnt lgkmcnt(6)
	v_mfma_f32_32x32x16_bf16 v[98:113], v[138:141], v[126:129], v[98:113]
	ds_read_b128 v[138:141], v168 offset:20096
	v_add_f32_e32 v173, v173, v196
	v_add_f32_e32 v174, v174, v197
	v_add_f32_e32 v173, v173, v198
	v_add_f32_e32 v174, v174, v199
	s_waitcnt lgkmcnt(6)
	v_mfma_f32_32x32x16_bf16 v[82:97], v[142:145], v[126:129], v[82:97]
	ds_read_b128 v[142:145], v168 offset:13472
	v_cvt_pk_bf16_f32 v184, v192, v193
	v_cvt_pk_bf16_f32 v185, v194, v195
	v_cvt_pk_bf16_f32 v186, v196, v197
	v_cvt_pk_bf16_f32 v187, v198, v199
	s_waitcnt lgkmcnt(6)
	v_mfma_f32_32x32x16_bf16 v[98:113], v[146:149], v[130:133], v[98:113]
	ds_read_b128 v[146:149], v168 offset:20128
	v_exp_f32_e32 v192, v74
	v_exp_f32_e32 v193, v75
	v_exp_f32_e32 v194, v76
	v_exp_f32_e32 v195, v77
	s_waitcnt lgkmcnt(5)
	v_mfma_f32_32x32x16_bf16 v[2:17], v[184:187], v[212:215], v[2:17]
	ds_read_b64_tr_b16 v[220:221], v170 offset:33536
	ds_read_b64_tr_b16 v[222:223], v170 offset:34688
	v_exp_f32_e32 v196, v78
	v_exp_f32_e32 v197, v79
	v_exp_f32_e32 v198, v80
	v_exp_f32_e32 v199, v81
	s_waitcnt lgkmcnt(5)
	v_mfma_f32_32x32x16_bf16 v[18:33], v[184:187], v[216:219], v[18:33]
	ds_read_b64_tr_b16 v[236:237], v170 offset:33600
	ds_read_b64_tr_b16 v[238:239], v170 offset:34752
	v_add_f32_e32 v173, v173, v192
	v_add_f32_e32 v174, v174, v193
	v_add_f32_e32 v173, v173, v194
	v_add_f32_e32 v174, v174, v195
	s_waitcnt lgkmcnt(6)
	v_mfma_f32_32x32x16_bf16 v[82:97], v[138:141], v[130:133], v[82:97]
	v_add_f32_e32 v173, v173, v196
	v_add_f32_e32 v174, v174, v197
	v_add_f32_e32 v173, v173, v198
	v_add_f32_e32 v174, v174, v199
	s_waitcnt lgkmcnt(5)
	v_mfma_f32_32x32x16_bf16 v[98:113], v[142:145], v[134:137], v[98:113]
	v_cvt_pk_bf16_f32 v188, v192, v193
	v_cvt_pk_bf16_f32 v189, v194, v195
	v_cvt_pk_bf16_f32 v190, v196, v197
	v_cvt_pk_bf16_f32 v191, v198, v199
	s_waitcnt lgkmcnt(4)
	v_mfma_f32_32x32x16_bf16 v[82:97], v[146:149], v[134:137], v[82:97]
	v_add_f32_e32 v172, v172, v173
	v_add_f32_e32 v172, v172, v174
	s_waitcnt lgkmcnt(2)
	v_mfma_f32_32x32x16_bf16 v[2:17], v[188:191], v[220:223], v[2:17]
	s_waitcnt vmcnt(3)
	ds_write_b128 v166, v[224:227]
	ds_write_b128 v167, v[232:235] offset:35840
	s_waitcnt lgkmcnt(2)
	v_mfma_f32_32x32x16_bf16 v[18:33], v[188:191], v[236:239], v[18:33]
	s_and_b64 vcc, exec, s[40:41]
	s_cbranch_vccz .Lattn_nok1_a
	ds_write_b128 v171, v[228:231]

; __device__ __forceinline__ void attn_unit(CArgs a, int layer, int unit, LAS unsigned char* lds) {
;     ...
;     auto tile = [&](int t, f32x16& c0, f32x16& c1, f32x16& n0, f32x16& n1) {
;         const int buf = t & 1;
;         gloadK(t + 2 < NT ? t + 2 : NT - 1); gloadV(t + 1 < NT ? t + 1 : NT - 1);
;         const LAS bf16_t* Vl = (const LAS bf16_t*)(lds + AT_V + buf * AT_VB);
;         if (t + 1 < NT) qk(buf ^ 1, n0, n1);
;         f32x16 p0, p1;
;         float rs = 0.f;
; #pragma unroll
;         for (int r = 0; r < 16; ++r) { p0[r] = __builtin_amdgcn_exp2f(c0[r]); p1[r] = __builtin_amdgcn_exp2f(c1[r]); rs += p0[r] + p1[r]; }
;         lrun += rs;
;         bf16x8 pf[4];
; #pragma unroll
;         for (int s = 0; s < 2; ++s) {
;             u32x4 w0, w1;
;             w0.x = cvt_pk_bf16(p0[8 * s], p0[8 * s + 1]); w0.y = cvt_pk_bf16(p0[8 * s + 2], p0[8 * s + 3]); w0.z = cvt_pk_bf16(p0[8 * s + 4], p0[8 * s + 5]); w0.w = cvt_pk_bf16(p0[8 * s + 6], p0[8 * s + 7]);
;             w1.x = cvt_pk_bf16(p1[8 * s], p1[8 * s + 1]); w1.y = cvt_pk_bf16(p1[8 * s + 2], p1[8 * s + 3]); w1.z = cvt_pk_bf16(p1[8 * s + 4], p1[8 * s + 5]); w1.w = cvt_pk_bf16(p1[8 * s + 6], p1[8 * s + 7]);
;             pf[s] = __builtin_bit_cast(bf16x8, w0); pf[2 + s] = __builtin_bit_cast(bf16x8, w1);
;         }
; #pragma unroll
;         for (int i = 0; i < 12; ++i) { __builtin_amdgcn_sched_group_barrier(0x008, 1, 0); __builtin_amdgcn_sched_group_barrier(0x002, 9, 0); }
; #pragma unroll
;         for (int s4 = 0; s4 < 4; ++s4) {
;             const int kb = 32 * (s4 >> 1) + 16 * (s4 & 1) + 4 * hi;
;             const LAS bf16_t* vrow = Vl + (kb - 4 * hi + 4 * hi + ((lane & 15) >> 2)) * AT_VLD + 16 * ((lane >> 4) & 1) + 4 * (lane & 3);
;             const v4i16_t a0 = __builtin_amdgcn_ds_read_tr16_b64_v4i16((LAS v4i16_t*)(vrow)), a1 = __builtin_amdgcn_ds_read_tr16_b64_v4i16((LAS v4i16_t*)(vrow + 8 * AT_VLD));
;             const v4i16_t c0 = __builtin_amdgcn_ds_read_tr16_b64_v4i16((LAS v4i16_t*)(vrow + 32)), c1 = __builtin_amdgcn_ds_read_tr16_b64_v4i16((LAS v4i16_t*)(vrow + 8 * AT_VLD + 32));
;             const bf16x8 v0 = __builtin_shufflevector(a0, a1, 0, 1, 2, 3, 4, 5, 6, 7), v1 = __builtin_shufflevector(c0, c1, 0, 1, 2, 3, 4, 5, 6, 7);
;             o0 = MFMA32(pf[s4], v0, o0);
;             o1 = MFMA32(pf[s4], v1, o1);
;         }
;         lstoreK(buf); lstoreV(buf ^ 1);
.Lattn_nok1_c:
	s_waitcnt lgkmcnt(0)
	s_barrier
	ds_read_b64_tr_b16 v[212:213], v170 offset:35840
	ds_read_b64_tr_b16 v[214:215], v170 offset:36992
	ds_read_b64_tr_b16 v[216:217], v170 offset:35904
	ds_read_b64_tr_b16 v[218:219], v170 offset:37056
	v_exp_f32_e32 v192, v98
	v_exp_f32_e32 v193, v99
	v_exp_f32_e32 v194, v100
	v_exp_f32_e32 v195, v101
	v_exp_f32_e32 v196, v102
	v_exp_f32_e32 v197, v103
	v_exp_f32_e32 v198, v104
	v_exp_f32_e32 v199, v105
	v_add_f32_e32 v173, v192, v193
	v_add_f32_e32 v174, v194, v195
	v_add_f32_e32 v173, v173, v196
	v_add_f32_e32 v174, v174, v197
	v_add_f32_e32 v173, v173, v198
	v_add_f32_e32 v174, v174, v199
	v_cvt_pk_bf16_f32 v176, v192, v193
	v_cvt_pk_bf16_f32 v177, v194, v195
	v_cvt_pk_bf16_f32 v178, v196, v197
	v_cvt_pk_bf16_f32 v179, v198, v199
	v_exp_f32_e32 v192, v106
	v_exp_f32_e32 v193, v107
	v_exp_f32_e32 v194, v108
	v_exp_f32_e32 v195, v109
	v_exp_f32_e32 v196, v110
	v_exp_f32_e32 v197, v111
	v_exp_f32_e32 v198, v112
	v_exp_f32_e32 v199, v113
	v_add_f32_e32 v173, v173, v192
	v_add_f32_e32 v174, v174, v193
	s_waitcnt lgkmcnt(2)
	v_mfma_f32_32x32x16_bf16 v[2:17], v[176:179], v[212:215], v[2:17]
	ds_read_b64_tr_b16 v[220:221], v170 offset:38144
	ds_read_b64_tr_b16 v[222:223], v170 offset:39296
	v_add_f32_e32 v173, v173, v194
	v_add_f32_e32 v174, v174, v195
	v_add_f32_e32 v173, v173, v196
	v_add_f32_e32 v174, v174, v197
	v_add_f32_e32 v173, v173, v198
	v_add_f32_e32 v174, v174, v199
	v_cvt_pk_bf16_f32 v180, v192, v193
	v_cvt_pk_bf16_f32 v181, v194, v195
	v_cvt_pk_bf16_f32 v182, v196, v197
	v_cvt_pk_bf16_f32 v183, v198, v199
	s_waitcnt lgkmcnt(2)
	v_mfma_f32_32x32x16_bf16 v[18:33], v[176:179], v[216:219], v[18:33]
	ds_read_b64_tr_b16 v[236:237], v170 offset:38208
	ds_read_b64_tr_b16 v[238:239], v170 offset:39360
	v_exp_f32_e32 v192, v82
	v_exp_f32_e32 v193, v83
	v_exp_f32_e32 v194, v84
	v_exp_f32_e32 v195, v85
	v_exp_f32_e32 v196, v86
	v_exp_f32_e32 v197, v87
	v_exp_f32_e32 v198, v88
	v_exp_f32_e32 v199, v89
	v_add_f32_e32 v173, v173, v192
	v_add_f32_e32 v174, v174, v193
	s_waitcnt lgkmcnt(2)
	v_mfma_f32_32x32x16_bf16 v[2:17], v[180:183], v[220:223], v[2:17]
	ds_read_b64_tr_b16 v[212:213], v170 offset:40448
	ds_read_b64_tr_b16 v[214:215], v170 offset:41600
	v_add_f32_e32 v173, v173, v194
	v_add_f32_e32 v174, v174, v195
	v_add_f32_e32 v173, v173, v196
	v_add_f32_e32 v174, v174, v197
	v_add_f32_e32 v173, v173, v198
	v_add_f32_e32 v174, v174, v199
	v_cvt_pk_bf16_f32 v184, v192, v193
	v_cvt_pk_bf16_f32 v185, v194, v195
	v_cvt_pk_bf16_f32 v186, v196, v197
	v_cvt_pk_bf16_f32 v187, v198, v199
	s_waitcnt lgkmcnt(2)
	v_mfma_f32_32x32x16_bf16 v[18:33], v[180:183], v[236:239], v[18:33]
	ds_read_b64_tr_b16 v[216:217], v170 offset:40512
	ds_read_b64_tr_b16 v[218:219], v170 offset:41664
	v_exp_f32_e32 v192, v90
	v_exp_f32_e32 v193, v91
	v_exp_f32_e32 v194, v92
	v_exp_f32_e32 v195, v93
	v_exp_f32_e32 v196, v94
	v_exp_f32_e32 v197, v95
	v_exp_f32_e32 v198, v96
	v_exp_f32_e32 v199, v97
	v_add_f32_e32 v173, v173, v192
	v_add_f32_e32 v174, v174, v193
	s_waitcnt lgkmcnt(2)
	v_mfma_f32_32x32x16_bf16 v[2:17], v[184:187], v[212:215], v[2:17]
	ds_read_b64_tr_b16 v[220:221], v170 offset:42752
	ds_read_b64_tr_b16 v[222:223], v170 offset:43904
	v_add_f32_e32 v173, v173, v194
	v_add_f32_e32 v174, v174, v195
	v_add_f32_e32 v173, v173, v196
	v_add_f32_e32 v174, v174, v197
	v_add_f32_e32 v173, v173, v198
	v_add_f32_e32 v174, v174, v199
	v_cvt_pk_bf16_f32 v188, v192, v193
	v_cvt_pk_bf16_f32 v189, v194, v195
	v_cvt_pk_bf16_f32 v190, v196, v197
	v_cvt_pk_bf16_f32 v191, v198, v199
	s_waitcnt lgkmcnt(2)
	v_mfma_f32_32x32x16_bf16 v[18:33], v[184:187], v[216:219], v[18:33]
	ds_read_b64_tr_b16 v[236:237], v170 offset:42816
	ds_read_b64_tr_b16 v[238:239], v170 offset:43968
	v_add_f32_e32 v172, v172, v173
	v_add_f32_e32 v172, v172, v174
	s_waitcnt lgkmcnt(2)
	v_mfma_f32_32x32x16_bf16 v[2:17], v[188:191], v[220:223], v[2:17]
	s_waitcnt lgkmcnt(0)
	v_mfma_f32_32x32x16_bf16 v[18:33], v[188:191], v[236:239], v[18:33]
	s_waitcnt lgkmcnt(0)
	s_barrier
	s_setprio 0
	s_nop 0
